# context-attention epilogue gate loads also issued up front; conv items in reverse wave order
# speedup vs baseline: 1.0012x; 1.0012x over previous
; DI void attn_task(const Params& P, int set, int b, int kvh, int qt, char* smem) {
;     ...
; #pragma unroll
;   for (int qi = 0; qi < 2; ++qi) {
;     const float ltot = l_run[qi] + __shfl_xor(l_run[qi], 32);
;     const float inv = 1.f / ltot;
;     const size_t row = row0 + 32 * qi;
; #pragma unroll
;     for (int db = 0; db < 2; ++db)
; #pragma unroll
;       for (int g = 0; g < 4; ++g) {
;         const size_t off = row * 512 + head * 64 + db * 32 + 8 * g + 4 * hh;
;         const half4 z = *(const half4*)(zs + off);
;         const f32x16& oo = o[qi][db];
;         *(half4*)(yc + row * LDY + head * 64 + db * 32 + 8 * g + 4 * hh) = cvt4(oo[4 * g] * inv * (float)z[0], oo[4 * g + 1] * inv * (float)z[1], oo[4 * g + 2] * inv * (float)z[2], oo[4 * g + 3] * inv * (float)z[3]);
;       }
;   }
.LBB0_81:
	v_readlane_b32 s2, v253, 31
	v_lshlrev_b32_e32 v128, 1, v174
	v_readlane_b32 s3, v253, 32
	v_lshlrev_b32_e32 v68, 3, v180
	v_mov_b32_e32 v69, v129
	v_lshl_add_u64 v[64:65], s[2:3], 0, v[128:129]
	v_readlane_b32 s2, v253, 33
	v_readlane_b32 s3, v253, 34
	v_lshl_add_u64 v[66:67], v[64:65], 0, v[68:69]
	v_mov_b32_e32 v216, v218
	v_lshl_add_u64 v[64:65], s[2:3], 0, v[128:129]
	v_lshl_add_u64 v[64:65], v[64:65], 0, v[68:69]
	ds_bpermute_b32 v68, v175, v169
	v_mad_u64_u32 v[64:65], s[2:3], v170, s4, v[64:65]
	v_mad_i32_i24 v65, v171, s4, v65
	s_waitcnt lgkmcnt(0)
	v_add_f32_e32 v68, v169, v68
	v_div_scale_f32 v69, s[2:3], v68, v68, 1.0
	v_rcp_f32_e32 v70, v69
	s_nop 0
	v_fma_f32 v71, -v69, v70, 1.0
	v_fmac_f32_e32 v70, v71, v70
	v_div_scale_f32 v71, vcc, 1.0, v68, 1.0
	v_mul_f32_e32 v72, v71, v70
	v_fma_f32 v73, -v69, v72, v71
	v_fmac_f32_e32 v72, v73, v70
	v_fma_f32 v69, -v69, v72, v71
	v_div_fmas_f32 v69, v69, v70, v72
	v_lshl_add_u64 v[70:71], v[66:67], 0, v[172:173]
	global_load_dwordx2 v[134:135], v[70:71], off
	global_load_dwordx2 v[136:137], v[70:71], off offset:16
	global_load_dwordx2 v[138:139], v[70:71], off offset:32
	global_load_dwordx2 v[140:141], v[70:71], off offset:48
	global_load_dwordx2 v[142:143], v[70:71], off offset:64
	global_load_dwordx2 v[144:145], v[70:71], off offset:80
	global_load_dwordx2 v[146:147], v[70:71], off offset:96
	global_load_dwordx2 v[148:149], v[70:71], off offset:112
	v_lshl_add_u64 v[132:133], v[66:67], 0, v[166:167]
	global_load_dwordx2 v[150:151], v[132:133], off
	global_load_dwordx2 v[152:153], v[132:133], off offset:16
	global_load_dwordx2 v[154:155], v[132:133], off offset:32
	global_load_dwordx2 v[156:157], v[132:133], off offset:48
	global_load_dwordx2 v[158:159], v[132:133], off offset:64
	global_load_dwordx2 v[160:161], v[132:133], off offset:80
	global_load_dwordx2 v[162:163], v[132:133], off offset:96
	global_load_dwordx2 v[164:165], v[132:133], off offset:112
	v_div_fixup_f32 v68, v69, v68, 1.0
	v_pk_mul_f32 v[48:49], v[48:49], v[68:69] op_sel_hi:[1,0]
	v_pk_mul_f32 v[50:51], v[50:51], v[68:69] op_sel_hi:[1,0]
	v_pk_mul_f32 v[32:33], v[32:33], v[68:69] op_sel_hi:[1,0]
	v_pk_mul_f32 v[34:35], v[34:35], v[68:69] op_sel_hi:[1,0]
	s_waitcnt vmcnt(0)
; DI void attn_task(const Params& P, int set, int b, int kvh, int qt, char* smem) {
;     ...
; #pragma unroll
;   for (int qi = 0; qi < 2; ++qi) {
;     const float ltot = l_run[qi] + __shfl_xor(l_run[qi], 32);
;     const float inv = 1.f / ltot;
;     const size_t row = row0 + 32 * qi;
; #pragma unroll
;     for (int db = 0; db < 2; ++db)
; #pragma unroll
;       for (int g = 0; g < 4; ++g) {
;         const size_t off = row * 512 + head * 64 + db * 32 + 8 * g + 4 * hh;
;         const half4 z = *(const half4*)(zs + off);
;         const f32x16& oo = o[qi][db];
;         *(half4*)(yc + row * LDY + head * 64 + db * 32 + 8 * g + 4 * hh) = cvt4(oo[4 * g] * inv * (float)z[0], oo[4 * g + 1] * inv * (float)z[1], oo[4 * g + 2] * inv * (float)z[2], oo[4 * g + 3] * inv * (float)z[3]);
;       }
;   }
	v_mov_b32_e32 v72, v134
	v_mov_b32_e32 v73, v135
	v_cvt_f32_f16_e32 v74, v72
	v_cvt_f32_f16_sdwa v75, v72 dst_sel:DWORD dst_unused:UNUSED_PAD src0_sel:WORD_1
	v_cvt_f32_f16_e32 v72, v73
	v_cvt_f32_f16_sdwa v73, v73 dst_sel:DWORD dst_unused:UNUSED_PAD src0_sel:WORD_1
	v_pk_mul_f32 v[48:49], v[48:49], v[74:75]
	s_nop 0
	v_cvt_pk_f16_f32 v48, v48, v49
	v_pk_mul_f32 v[50:51], v[50:51], v[72:73]
	s_nop 0
	v_cvt_pk_f16_f32 v49, v50, v51
	global_store_dwordx2 v[64:65], v[48:49], off
	v_mov_b32_e32 v48, v136
	v_mov_b32_e32 v49, v137
	v_pk_mul_f32 v[50:51], v[52:53], v[68:69] op_sel_hi:[1,0]
	v_cvt_f32_f16_e32 v52, v48
	v_cvt_f32_f16_sdwa v53, v48 dst_sel:DWORD dst_unused:UNUSED_PAD src0_sel:WORD_1
	v_pk_mul_f32 v[50:51], v[50:51], v[52:53]
	v_cvt_f32_f16_e32 v52, v49
	v_cvt_f32_f16_sdwa v53, v49 dst_sel:DWORD dst_unused:UNUSED_PAD src0_sel:WORD_1
	v_cvt_pk_f16_f32 v48, v50, v51
	v_pk_mul_f32 v[50:51], v[54:55], v[68:69] op_sel_hi:[1,0]
	s_nop 0
	v_pk_mul_f32 v[50:51], v[50:51], v[52:53]
	s_nop 0
	v_cvt_pk_f16_f32 v49, v50, v51
	global_store_dwordx2 v[64:65], v[48:49], off offset:16
	v_mov_b32_e32 v48, v138
	v_mov_b32_e32 v49, v139
	v_pk_mul_f32 v[50:51], v[56:57], v[68:69] op_sel_hi:[1,0]
	v_cvt_f32_f16_e32 v52, v48
	v_cvt_f32_f16_sdwa v53, v48 dst_sel:DWORD dst_unused:UNUSED_PAD src0_sel:WORD_1
	v_pk_mul_f32 v[50:51], v[50:51], v[52:53]
	v_cvt_f32_f16_e32 v52, v49
	v_cvt_f32_f16_sdwa v53, v49 dst_sel:DWORD dst_unused:UNUSED_PAD src0_sel:WORD_1
	v_cvt_pk_f16_f32 v48, v50, v51
	v_pk_mul_f32 v[50:51], v[58:59], v[68:69] op_sel_hi:[1,0]
	s_nop 0
	v_pk_mul_f32 v[50:51], v[50:51], v[52:53]
	s_nop 0
	v_cvt_pk_f16_f32 v49, v50, v51
	global_store_dwordx2 v[64:65], v[48:49], off offset:32
	v_mov_b32_e32 v48, v140
	v_mov_b32_e32 v49, v141
	v_pk_mul_f32 v[50:51], v[60:61], v[68:69] op_sel_hi:[1,0]
	v_cvt_f32_f16_e32 v52, v48
	v_cvt_f32_f16_sdwa v53, v48 dst_sel:DWORD dst_unused:UNUSED_PAD src0_sel:WORD_1
	v_pk_mul_f32 v[50:51], v[50:51], v[52:53]
	v_cvt_f32_f16_e32 v52, v49
	v_cvt_f32_f16_sdwa v53, v49 dst_sel:DWORD dst_unused:UNUSED_PAD src0_sel:WORD_1
	v_cvt_pk_f16_f32 v48, v50, v51
	v_pk_mul_f32 v[50:51], v[62:63], v[68:69] op_sel_hi:[1,0]
	s_nop 0
	v_pk_mul_f32 v[50:51], v[50:51], v[52:53]
	s_nop 0
	v_cvt_pk_f16_f32 v49, v50, v51
	global_store_dwordx2 v[64:65], v[48:49], off offset:48
	v_mov_b32_e32 v48, v142
	v_mov_b32_e32 v49, v143
	v_cvt_f32_f16_e32 v50, v48
	v_cvt_f32_f16_sdwa v51, v48 dst_sel:DWORD dst_unused:UNUSED_PAD src0_sel:WORD_1
	v_cvt_f32_f16_e32 v48, v49
	v_cvt_f32_f16_sdwa v49, v49 dst_sel:DWORD dst_unused:UNUSED_PAD src0_sel:WORD_1
	v_pk_mul_f32 v[32:33], v[32:33], v[50:51]
	s_nop 0
	v_cvt_pk_f16_f32 v32, v32, v33
	v_pk_mul_f32 v[34:35], v[34:35], v[48:49]
	s_nop 0
	v_cvt_pk_f16_f32 v33, v34, v35
	global_store_dwordx2 v[64:65], v[32:33], off offset:64
	v_mov_b32_e32 v32, v144
	v_mov_b32_e32 v33, v145
	v_pk_mul_f32 v[34:35], v[36:37], v[68:69] op_sel_hi:[1,0]
	v_cvt_f32_f16_e32 v36, v32
	v_cvt_f32_f16_sdwa v37, v32 dst_sel:DWORD dst_unused:UNUSED_PAD src0_sel:WORD_1
	v_pk_mul_f32 v[34:35], v[34:35], v[36:37]
	v_cvt_f32_f16_e32 v36, v33
	v_cvt_f32_f16_sdwa v37, v33 dst_sel:DWORD dst_unused:UNUSED_PAD src0_sel:WORD_1
	v_cvt_pk_f16_f32 v32, v34, v35
	v_pk_mul_f32 v[34:35], v[38:39], v[68:69] op_sel_hi:[1,0]
	s_nop 0
	v_pk_mul_f32 v[34:35], v[34:35], v[36:37]
	s_nop 0
	v_cvt_pk_f16_f32 v33, v34, v35
	global_store_dwordx2 v[64:65], v[32:33], off offset:80
	v_mov_b32_e32 v32, v146
	v_mov_b32_e32 v33, v147
	v_pk_mul_f32 v[34:35], v[40:41], v[68:69] op_sel_hi:[1,0]
	v_cvt_f32_f16_e32 v36, v32
	v_cvt_f32_f16_sdwa v37, v32 dst_sel:DWORD dst_unused:UNUSED_PAD src0_sel:WORD_1
	v_pk_mul_f32 v[34:35], v[34:35], v[36:37]
	v_cvt_f32_f16_e32 v36, v33
	v_cvt_f32_f16_sdwa v37, v33 dst_sel:DWORD dst_unused:UNUSED_PAD src0_sel:WORD_1
	v_cvt_pk_f16_f32 v32, v34, v35
	v_pk_mul_f32 v[34:35], v[42:43], v[68:69] op_sel_hi:[1,0]
	s_nop 0
	v_pk_mul_f32 v[34:35], v[34:35], v[36:37]
	s_nop 0
	v_cvt_pk_f16_f32 v33, v34, v35
	global_store_dwordx2 v[64:65], v[32:33], off offset:96
	v_mov_b32_e32 v32, v148
	v_mov_b32_e32 v33, v149
	v_pk_mul_f32 v[34:35], v[44:45], v[68:69] op_sel_hi:[1,0]
	v_cvt_f32_f16_e32 v36, v32
	v_cvt_f32_f16_sdwa v37, v32 dst_sel:DWORD dst_unused:UNUSED_PAD src0_sel:WORD_1
	v_pk_mul_f32 v[34:35], v[34:35], v[36:37]
	v_cvt_f32_f16_e32 v36, v33
	v_cvt_f32_f16_sdwa v37, v33 dst_sel:DWORD dst_unused:UNUSED_PAD src0_sel:WORD_1
	v_cvt_pk_f16_f32 v32, v34, v35
	v_pk_mul_f32 v[34:35], v[46:47], v[68:69] op_sel_hi:[1,0]
	s_nop 0
	v_pk_mul_f32 v[34:35], v[34:35], v[36:37]
	s_nop 0
	v_cvt_pk_f16_f32 v33, v34, v35
	global_store_dwordx2 v[64:65], v[32:33], off offset:112
	ds_bpermute_b32 v32, v175, v168
	s_waitcnt lgkmcnt(0)
	v_add_f32_e32 v32, v168, v32
	v_div_scale_f32 v33, s[2:3], v32, v32, 1.0
	v_rcp_f32_e32 v34, v33
	s_mov_b64 s[2:3], 0x9000
	v_fma_f32 v35, -v33, v34, 1.0
	v_fmac_f32_e32 v34, v35, v34
	v_div_scale_f32 v35, vcc, 1.0, v32, 1.0
	v_mul_f32_e32 v36, v35, v34
	v_fma_f32 v37, -v33, v36, v35
	v_fmac_f32_e32 v36, v37, v34
	v_fma_f32 v33, -v33, v36, v35
	v_div_fmas_f32 v33, v33, v34, v36
	v_lshl_add_u64 v[34:35], v[66:67], 0, v[166:167]
	v_mov_b32_e32 v38, v150
	v_mov_b32_e32 v39, v151
	v_div_fixup_f32 v32, v33, v32, 1.0
	v_pk_mul_f32 v[16:17], v[16:17], v[32:33] op_sel_hi:[1,0]
	v_pk_mul_f32 v[18:19], v[18:19], v[32:33] op_sel_hi:[1,0]
	v_lshl_add_u64 v[36:37], v[64:65], 0, s[2:3]
	s_mov_b64 s[2:3], 0
	v_cvt_f32_f16_e32 v40, v38
	v_cvt_f32_f16_sdwa v41, v38 dst_sel:DWORD dst_unused:UNUSED_PAD src0_sel:WORD_1
	v_cvt_f32_f16_e32 v38, v39
	v_cvt_f32_f16_sdwa v39, v39 dst_sel:DWORD dst_unused:UNUSED_PAD src0_sel:WORD_1
	v_pk_mul_f32 v[16:17], v[16:17], v[40:41]
	s_nop 0
	v_cvt_pk_f16_f32 v16, v16, v17
	v_pk_mul_f32 v[18:19], v[18:19], v[38:39]
	s_nop 0
	v_cvt_pk_f16_f32 v17, v18, v19
	v_add_co_u32_e32 v18, vcc, 0x9000, v64
	s_nop 1
	v_addc_co_u32_e32 v19, vcc, 0, v65, vcc
	global_store_dwordx2 v[18:19], v[16:17], off
